# phase 1 big tiles: cyclic per-block K start (spreads L2 channel load)
# baseline (speedup 1.0000x reference)
.LBB0_116:
	s_or_b64 exec, exec, s[0:1]
	s_add_u32 s0, s94, 0x15000000
	s_addc_u32 s1, s95, 0
	s_add_u32 s28, s94, 0x6c00000
	v_writelane_b32 v242, s0, 50
	s_addc_u32 s29, s95, 0
	v_mov_b32_e32 v0, v199
	v_writelane_b32 v242, s1, 51
	s_add_u32 s0, s94, 0xd000000
	s_addc_u32 s1, s95, 0
	v_writelane_b32 v242, s0, 52
	s_barrier
	s_nop 0
	v_writelane_b32 v242, s1, 53
	s_nop 0
	v_readlane_b32 s0, v242, 45
	v_readlane_b32 s1, v242, 46
	s_cmpk_gt_i32 s0, 0x29ff
	v_writelane_b32 v242, s58, 54
	s_nop 1
	v_writelane_b32 v242, s59, 55
	s_cbranch_scc1 .LBB0_246
	s_mov_b32 s91, 0
	s_cmp_lg_u32 s96, 0x200
	s_cbranch_scc1 .Lbig_skip
	v_lshrrev_b32_e32 v236, 3, v199
	v_lshrrev_b32_e32 v237, 4, v199
	v_xor_b32_e32 v237, v237, v199
	v_and_b32_e32 v237, 7, v237
	v_lshlrev_b32_e32 v237, 4, v237
	v_lshl_add_u32 v192, v236, 12, v237
	v_add_u32_e32 v193, 0x20000, v192
	v_add_u32_e32 v194, 0x40000, v192
	v_add_u32_e32 v195, 0x60000, v192
	v_and_b32_e32 v236, 15, v199
	v_bfe_u32 v237, v199, 4, 2
	v_lshrrev_b32_e32 v238, 1, v236
	v_lshlrev_b32_e32 v202, 3, v237
	v_xor_b32_e32 v237, v237, v238
	v_lshlrev_b32_e32 v237, 4, v237
	v_xor_b32_e32 v238, 64, v237
	v_lshrrev_b32_e32 v201, 7, v199
	v_lshl_add_u32 v201, v201, 7, v236
	v_lshlrev_b32_e32 v196, 7, v201
	v_bfe_u32 v198, v199, 6, 1
	v_lshl_add_u32 v202, v198, 7, v202
	v_lshl_add_u32 v198, v198, 6, v236
	v_lshlrev_b32_e32 v198, 7, v198
	v_add_u32_e32 v198, 0x8000, v198
	v_add_u32_e32 v197, v196, v238
	v_add_u32_e32 v200, v198, v238
	v_add_u32_e32 v196, v196, v237
	v_add_u32_e32 v198, v198, v237
	v_lshrrev_b32_e32 v236, 6, v199
	v_lshlrev_b32_e32 v236, 10, v236
	s_nop 0
	v_readfirstlane_b32 s32, v236
	v_readlane_b32 s90, v242, 45
	s_and_b32 s51, s90, 63
	s_lshl_b32 s51, s51, 20
	s_add_u32 s36, s94, s51
	s_addc_u32 s37, s95, 0
	s_add_u32 s36, s36, 0x15000000
	s_addc_u32 s37, s37, 0
	s_lshr_b32 s51, s90, 6
	s_lshl_b32 s51, s51, 19
	s_add_u32 s44, s94, s51
	s_addc_u32 s45, s95, 0
	s_add_u32 s44, s44, 0x19000000
	s_addc_u32 s45, s45, 0
	s_add_u32 s40, s36, 0x80000
	s_addc_u32 s41, s37, 0
	s_and_b32 s21, s90, 31
	s_mov_b32 s20, s21
	s_lshl_b32 s51, s21, 7
	s_add_u32 s36, s36, s51
	s_addc_u32 s37, s37, 0
	s_add_u32 s40, s40, s51
	s_addc_u32 s41, s41, 0
	s_add_u32 s44, s44, s51
	s_addc_u32 s45, s45, 0
	s_barrier
	s_add_u32 m0, s32, 0x0
	s_nop 0
	global_load_lds_dwordx4 v192, s[36:37]
	s_add_u32 m0, s32, 0x1000
	s_nop 0
	global_load_lds_dwordx4 v193, s[36:37]
	s_add_u32 m0, s32, 0x2000
	s_nop 0
	global_load_lds_dwordx4 v194, s[36:37]
	s_add_u32 m0, s32, 0x3000
	s_nop 0
	global_load_lds_dwordx4 v195, s[36:37]
	s_add_u32 m0, s32, 0x4000
	s_nop 0
	global_load_lds_dwordx4 v192, s[40:41]
	s_add_u32 m0, s32, 0x5000
	s_nop 0
	global_load_lds_dwordx4 v193, s[40:41]
	s_add_u32 m0, s32, 0x6000
	s_nop 0
	global_load_lds_dwordx4 v194, s[40:41]
	s_add_u32 m0, s32, 0x7000
	s_nop 0
	global_load_lds_dwordx4 v195, s[40:41]
	s_add_u32 m0, s32, 0x8000
	s_nop 0
	global_load_lds_dwordx4 v192, s[44:45]
	s_add_u32 m0, s32, 0x9000
	s_nop 0
	global_load_lds_dwordx4 v193, s[44:45]
	s_add_u32 m0, s32, 0xa000
	s_nop 0
	global_load_lds_dwordx4 v194, s[44:45]
	s_add_u32 m0, s32, 0xb000
	s_nop 0
	global_load_lds_dwordx4 v195, s[44:45]
	s_add_u32 s36, s36, 0x80
	s_addc_u32 s37, s37, 0
	s_add_u32 s40, s40, 0x80
	s_addc_u32 s41, s41, 0
	s_add_u32 s44, s44, 0x80
	s_addc_u32 s45, s45, 0
	s_add_i32 s20, s20, 1
	s_cmp_eq_u32 s20, 32
	s_cbranch_scc1 .Lbig_wrap0

.Lbig_tile:
	s_add_u32 s91, s90, 0x200
	s_and_b32 s51, s91, 63
	s_lshl_b32 s51, s51, 20
	s_add_u32 s46, s94, s51
	s_addc_u32 s47, s95, 0
	s_add_u32 s46, s46, 0x15000000
	s_addc_u32 s47, s47, 0
	s_lshr_b32 s51, s91, 6
	s_lshl_b32 s51, s51, 19
	s_add_u32 s48, s94, s51
	s_addc_u32 s49, s95, 0
	s_add_u32 s48, s48, 0x19000000
	s_addc_u32 s49, s49, 0
	s_lshl_b32 s51, s21, 7
	s_add_u32 s46, s46, s51
	s_addc_u32 s47, s47, 0
	s_add_u32 s48, s48, s51
	s_addc_u32 s49, s49, 0
	v_mov_b32_e32 v0, 0
	v_mov_b32_e32 v1, 0
	v_mov_b32_e32 v2, 0
	v_mov_b32_e32 v3, 0
	v_mov_b32_e32 v4, 0
	v_mov_b32_e32 v5, 0
	v_mov_b32_e32 v6, 0
	v_mov_b32_e32 v7, 0
	v_mov_b32_e32 v8, 0
	v_mov_b32_e32 v9, 0
	v_mov_b32_e32 v10, 0
	v_mov_b32_e32 v11, 0
	v_mov_b32_e32 v12, 0
	v_mov_b32_e32 v13, 0
	v_mov_b32_e32 v14, 0
	v_mov_b32_e32 v15, 0
	v_mov_b32_e32 v16, 0
	v_mov_b32_e32 v17, 0
	v_mov_b32_e32 v18, 0
	v_mov_b32_e32 v19, 0
	v_mov_b32_e32 v20, 0
	v_mov_b32_e32 v21, 0
	v_mov_b32_e32 v22, 0
	v_mov_b32_e32 v23, 0
	v_mov_b32_e32 v24, 0
	v_mov_b32_e32 v25, 0
	v_mov_b32_e32 v26, 0
	v_mov_b32_e32 v27, 0
	v_mov_b32_e32 v28, 0
	v_mov_b32_e32 v29, 0
	v_mov_b32_e32 v30, 0
	v_mov_b32_e32 v31, 0
	v_mov_b32_e32 v32, 0
	v_mov_b32_e32 v33, 0
	v_mov_b32_e32 v34, 0
	v_mov_b32_e32 v35, 0
	v_mov_b32_e32 v36, 0
	v_mov_b32_e32 v37, 0
	v_mov_b32_e32 v38, 0
	v_mov_b32_e32 v39, 0
	v_mov_b32_e32 v40, 0
	v_mov_b32_e32 v41, 0
	v_mov_b32_e32 v42, 0
	v_mov_b32_e32 v43, 0
	v_mov_b32_e32 v44, 0
	v_mov_b32_e32 v45, 0
	v_mov_b32_e32 v46, 0
	v_mov_b32_e32 v47, 0
	v_mov_b32_e32 v48, 0
	v_mov_b32_e32 v49, 0
	v_mov_b32_e32 v50, 0
	v_mov_b32_e32 v51, 0
	v_mov_b32_e32 v52, 0
	v_mov_b32_e32 v53, 0
	v_mov_b32_e32 v54, 0
	v_mov_b32_e32 v55, 0
	v_mov_b32_e32 v56, 0
	v_mov_b32_e32 v57, 0
	v_mov_b32_e32 v58, 0
	v_mov_b32_e32 v59, 0
	v_mov_b32_e32 v60, 0
	v_mov_b32_e32 v61, 0
	v_mov_b32_e32 v62, 0
	v_mov_b32_e32 v63, 0
	v_mov_b32_e32 v64, 0
	v_mov_b32_e32 v65, 0
	v_mov_b32_e32 v66, 0
	v_mov_b32_e32 v67, 0
	v_mov_b32_e32 v68, 0
	v_mov_b32_e32 v69, 0
	v_mov_b32_e32 v70, 0
	v_mov_b32_e32 v71, 0
	v_mov_b32_e32 v72, 0
	v_mov_b32_e32 v73, 0
	v_mov_b32_e32 v74, 0
	v_mov_b32_e32 v75, 0
	v_mov_b32_e32 v76, 0
	v_mov_b32_e32 v77, 0
	v_mov_b32_e32 v78, 0
	v_mov_b32_e32 v79, 0
	v_mov_b32_e32 v80, 0
	v_mov_b32_e32 v81, 0
	v_mov_b32_e32 v82, 0
	v_mov_b32_e32 v83, 0
	v_mov_b32_e32 v84, 0
	v_mov_b32_e32 v85, 0
	v_mov_b32_e32 v86, 0
	v_mov_b32_e32 v87, 0
	v_mov_b32_e32 v88, 0
	v_mov_b32_e32 v89, 0
	v_mov_b32_e32 v90, 0
	v_mov_b32_e32 v91, 0
	v_mov_b32_e32 v92, 0
	v_mov_b32_e32 v93, 0
	v_mov_b32_e32 v94, 0
	v_mov_b32_e32 v95, 0
	v_mov_b32_e32 v96, 0
	v_mov_b32_e32 v97, 0
	v_mov_b32_e32 v98, 0
	v_mov_b32_e32 v99, 0
	v_mov_b32_e32 v100, 0
	v_mov_b32_e32 v101, 0
	v_mov_b32_e32 v102, 0
	v_mov_b32_e32 v103, 0
	v_mov_b32_e32 v104, 0
	v_mov_b32_e32 v105, 0
	v_mov_b32_e32 v106, 0
	v_mov_b32_e32 v107, 0
	v_mov_b32_e32 v108, 0
	v_mov_b32_e32 v109, 0
	v_mov_b32_e32 v110, 0
	v_mov_b32_e32 v111, 0
	v_mov_b32_e32 v112, 0
	v_mov_b32_e32 v113, 0
	v_mov_b32_e32 v114, 0
	v_mov_b32_e32 v115, 0
	v_mov_b32_e32 v116, 0
	v_mov_b32_e32 v117, 0
	v_mov_b32_e32 v118, 0
	v_mov_b32_e32 v119, 0
	v_mov_b32_e32 v120, 0
	v_mov_b32_e32 v121, 0
	v_mov_b32_e32 v122, 0
	v_mov_b32_e32 v123, 0
	v_mov_b32_e32 v124, 0
	v_mov_b32_e32 v125, 0
	v_mov_b32_e32 v126, 0
	v_mov_b32_e32 v127, 0
	s_mov_b32 s50, 0
	s_waitcnt vmcnt(32)
	s_branch .Lbig_k_in

.Lbig_k_in:
	s_barrier
	ds_read_b128 v[160:163], v198 offset:0
	ds_read_b128 v[164:167], v198 offset:2048
	ds_read_b128 v[168:171], v198 offset:4096
	ds_read_b128 v[172:175], v198 offset:6144
	ds_read_b128 v[128:131], v196 offset:0
	ds_read_b128 v[132:135], v196 offset:2048
	ds_read_b128 v[136:139], v196 offset:4096
	ds_read_b128 v[140:143], v196 offset:6144
	ds_read_b128 v[144:147], v196 offset:8192
	ds_read_b128 v[148:151], v196 offset:10240
	ds_read_b128 v[152:155], v196 offset:12288
	ds_read_b128 v[156:159], v196 offset:14336
	ds_read_b128 v[176:179], v200 offset:0
	ds_read_b128 v[180:183], v200 offset:2048
	ds_read_b128 v[184:187], v200 offset:4096
	ds_read_b128 v[188:191], v200 offset:6144
	ds_read_b128 v[204:207], v197 offset:0
	ds_read_b128 v[208:211], v197 offset:2048
	ds_read_b128 v[212:215], v197 offset:4096
	ds_read_b128 v[216:219], v197 offset:6144
	ds_read_b128 v[220:223], v197 offset:8192
	ds_read_b128 v[224:227], v197 offset:10240
	ds_read_b128 v[228:231], v197 offset:12288
	ds_read_b128 v[232:235], v197 offset:14336
	s_waitcnt lgkmcnt(0)
	s_barrier
	s_add_u32 m0, s32, 0x0
	s_nop 0
	global_load_lds_dwordx4 v192, s[36:37]
	s_add_u32 m0, s32, 0x1000
	s_nop 0
	global_load_lds_dwordx4 v193, s[36:37]
	s_add_u32 m0, s32, 0x2000
	s_nop 0
	global_load_lds_dwordx4 v194, s[36:37]
	s_add_u32 m0, s32, 0x3000
	s_nop 0
	global_load_lds_dwordx4 v195, s[36:37]
	s_add_u32 m0, s32, 0x4000
	s_nop 0
	global_load_lds_dwordx4 v192, s[40:41]
	s_add_u32 m0, s32, 0x5000
	s_nop 0
	global_load_lds_dwordx4 v193, s[40:41]
	s_add_u32 m0, s32, 0x6000
	s_nop 0
	global_load_lds_dwordx4 v194, s[40:41]
	s_add_u32 m0, s32, 0x7000
	s_nop 0
	global_load_lds_dwordx4 v195, s[40:41]
	s_add_u32 m0, s32, 0x8000
	s_nop 0
	global_load_lds_dwordx4 v192, s[44:45]
	s_add_u32 m0, s32, 0x9000
	s_nop 0
	global_load_lds_dwordx4 v193, s[44:45]
	s_add_u32 m0, s32, 0xa000
	s_nop 0
	global_load_lds_dwordx4 v194, s[44:45]
	s_add_u32 m0, s32, 0xb000
	s_nop 0
	global_load_lds_dwordx4 v195, s[44:45]
	s_add_u32 s36, s36, 0x80
	s_addc_u32 s37, s37, 0
	s_add_u32 s40, s40, 0x80
	s_addc_u32 s41, s41, 0
	s_add_u32 s44, s44, 0x80
	s_addc_u32 s45, s45, 0
	s_add_i32 s20, s20, 1
	s_cmp_eq_u32 s20, 32
	s_cbranch_scc1 .Lbig_wrap1
.Lbig_wrapret1:
	s_setprio 1
	v_mfma_f32_16x16x32_bf16 v[0:3], v[160:163], v[128:131], v[0:3]
	v_mfma_f32_16x16x32_bf16 v[4:7], v[164:167], v[128:131], v[4:7]
	v_mfma_f32_16x16x32_bf16 v[8:11], v[168:171], v[128:131], v[8:11]
	v_mfma_f32_16x16x32_bf16 v[12:15], v[172:175], v[128:131], v[12:15]
	v_mfma_f32_16x16x32_bf16 v[16:19], v[160:163], v[132:135], v[16:19]
	v_mfma_f32_16x16x32_bf16 v[20:23], v[164:167], v[132:135], v[20:23]
	v_mfma_f32_16x16x32_bf16 v[24:27], v[168:171], v[132:135], v[24:27]
	v_mfma_f32_16x16x32_bf16 v[28:31], v[172:175], v[132:135], v[28:31]
	v_mfma_f32_16x16x32_bf16 v[32:35], v[160:163], v[136:139], v[32:35]
	v_mfma_f32_16x16x32_bf16 v[36:39], v[164:167], v[136:139], v[36:39]
	v_mfma_f32_16x16x32_bf16 v[40:43], v[168:171], v[136:139], v[40:43]
	v_mfma_f32_16x16x32_bf16 v[44:47], v[172:175], v[136:139], v[44:47]
	v_mfma_f32_16x16x32_bf16 v[48:51], v[160:163], v[140:143], v[48:51]
	v_mfma_f32_16x16x32_bf16 v[52:55], v[164:167], v[140:143], v[52:55]
	v_mfma_f32_16x16x32_bf16 v[56:59], v[168:171], v[140:143], v[56:59]
	v_mfma_f32_16x16x32_bf16 v[60:63], v[172:175], v[140:143], v[60:63]
	v_mfma_f32_16x16x32_bf16 v[64:67], v[160:163], v[144:147], v[64:67]
	v_mfma_f32_16x16x32_bf16 v[68:71], v[164:167], v[144:147], v[68:71]
	v_mfma_f32_16x16x32_bf16 v[72:75], v[168:171], v[144:147], v[72:75]
	v_mfma_f32_16x16x32_bf16 v[76:79], v[172:175], v[144:147], v[76:79]
	v_mfma_f32_16x16x32_bf16 v[80:83], v[160:163], v[148:151], v[80:83]
	v_mfma_f32_16x16x32_bf16 v[84:87], v[164:167], v[148:151], v[84:87]
	v_mfma_f32_16x16x32_bf16 v[88:91], v[168:171], v[148:151], v[88:91]
	v_mfma_f32_16x16x32_bf16 v[92:95], v[172:175], v[148:151], v[92:95]
	v_mfma_f32_16x16x32_bf16 v[96:99], v[160:163], v[152:155], v[96:99]
	v_mfma_f32_16x16x32_bf16 v[100:103], v[164:167], v[152:155], v[100:103]
	v_mfma_f32_16x16x32_bf16 v[104:107], v[168:171], v[152:155], v[104:107]
	v_mfma_f32_16x16x32_bf16 v[108:111], v[172:175], v[152:155], v[108:111]
	v_mfma_f32_16x16x32_bf16 v[112:115], v[160:163], v[156:159], v[112:115]
	v_mfma_f32_16x16x32_bf16 v[116:119], v[164:167], v[156:159], v[116:119]
	v_mfma_f32_16x16x32_bf16 v[120:123], v[168:171], v[156:159], v[120:123]
	v_mfma_f32_16x16x32_bf16 v[124:127], v[172:175], v[156:159], v[124:127]
	v_mfma_f32_16x16x32_bf16 v[0:3], v[176:179], v[204:207], v[0:3]
	v_mfma_f32_16x16x32_bf16 v[4:7], v[180:183], v[204:207], v[4:7]
	v_mfma_f32_16x16x32_bf16 v[8:11], v[184:187], v[204:207], v[8:11]
	v_mfma_f32_16x16x32_bf16 v[12:15], v[188:191], v[204:207], v[12:15]
	v_mfma_f32_16x16x32_bf16 v[16:19], v[176:179], v[208:211], v[16:19]
	v_mfma_f32_16x16x32_bf16 v[20:23], v[180:183], v[208:211], v[20:23]
	v_mfma_f32_16x16x32_bf16 v[24:27], v[184:187], v[208:211], v[24:27]
	v_mfma_f32_16x16x32_bf16 v[28:31], v[188:191], v[208:211], v[28:31]
	v_mfma_f32_16x16x32_bf16 v[32:35], v[176:179], v[212:215], v[32:35]
	v_mfma_f32_16x16x32_bf16 v[36:39], v[180:183], v[212:215], v[36:39]
	v_mfma_f32_16x16x32_bf16 v[40:43], v[184:187], v[212:215], v[40:43]
	v_mfma_f32_16x16x32_bf16 v[44:47], v[188:191], v[212:215], v[44:47]
	v_mfma_f32_16x16x32_bf16 v[48:51], v[176:179], v[216:219], v[48:51]
	v_mfma_f32_16x16x32_bf16 v[52:55], v[180:183], v[216:219], v[52:55]
	v_mfma_f32_16x16x32_bf16 v[56:59], v[184:187], v[216:219], v[56:59]
	v_mfma_f32_16x16x32_bf16 v[60:63], v[188:191], v[216:219], v[60:63]
	v_mfma_f32_16x16x32_bf16 v[64:67], v[176:179], v[220:223], v[64:67]
	v_mfma_f32_16x16x32_bf16 v[68:71], v[180:183], v[220:223], v[68:71]
	v_mfma_f32_16x16x32_bf16 v[72:75], v[184:187], v[220:223], v[72:75]
	v_mfma_f32_16x16x32_bf16 v[76:79], v[188:191], v[220:223], v[76:79]
	v_mfma_f32_16x16x32_bf16 v[80:83], v[176:179], v[224:227], v[80:83]
	v_mfma_f32_16x16x32_bf16 v[84:87], v[180:183], v[224:227], v[84:87]
	v_mfma_f32_16x16x32_bf16 v[88:91], v[184:187], v[224:227], v[88:91]
	v_mfma_f32_16x16x32_bf16 v[92:95], v[188:191], v[224:227], v[92:95]
	v_mfma_f32_16x16x32_bf16 v[96:99], v[176:179], v[228:231], v[96:99]
	v_mfma_f32_16x16x32_bf16 v[100:103], v[180:183], v[228:231], v[100:103]
	v_mfma_f32_16x16x32_bf16 v[104:107], v[184:187], v[228:231], v[104:107]
	v_mfma_f32_16x16x32_bf16 v[108:111], v[188:191], v[228:231], v[108:111]
	v_mfma_f32_16x16x32_bf16 v[112:115], v[176:179], v[232:235], v[112:115]
	v_mfma_f32_16x16x32_bf16 v[116:119], v[180:183], v[232:235], v[116:119]
	v_mfma_f32_16x16x32_bf16 v[120:123], v[184:187], v[232:235], v[120:123]
	v_mfma_f32_16x16x32_bf16 v[124:127], v[188:191], v[232:235], v[124:127]
	s_setprio 0
	s_add_i32 s50, s50, 1
	s_cmp_lt_u32 s50, 31
	s_cbranch_scc1 .Lbig_k
	s_waitcnt vmcnt(0)
	s_barrier
	ds_read_b128 v[160:163], v198 offset:0
	ds_read_b128 v[164:167], v198 offset:2048
	ds_read_b128 v[168:171], v198 offset:4096
	ds_read_b128 v[172:175], v198 offset:6144
	ds_read_b128 v[128:131], v196 offset:0
	ds_read_b128 v[132:135], v196 offset:2048
	ds_read_b128 v[136:139], v196 offset:4096
	ds_read_b128 v[140:143], v196 offset:6144
	ds_read_b128 v[144:147], v196 offset:8192
	ds_read_b128 v[148:151], v196 offset:10240
	ds_read_b128 v[152:155], v196 offset:12288
	ds_read_b128 v[156:159], v196 offset:14336
	ds_read_b128 v[176:179], v200 offset:0
	ds_read_b128 v[180:183], v200 offset:2048
	ds_read_b128 v[184:187], v200 offset:4096
	ds_read_b128 v[188:191], v200 offset:6144
	ds_read_b128 v[204:207], v197 offset:0
	ds_read_b128 v[208:211], v197 offset:2048
	ds_read_b128 v[212:215], v197 offset:4096
	ds_read_b128 v[216:219], v197 offset:6144
	ds_read_b128 v[220:223], v197 offset:8192
	ds_read_b128 v[224:227], v197 offset:10240
	ds_read_b128 v[228:231], v197 offset:12288
	ds_read_b128 v[232:235], v197 offset:14336
	s_waitcnt lgkmcnt(0)
	s_cmp_ge_u32 s91, 0x1400
	s_cbranch_scc1 .Lbig_nonext
	s_barrier
	s_mov_b64 s[36:37], s[46:47]
	s_mov_b64 s[44:45], s[48:49]
	s_add_u32 s40, s36, 0x80000
	s_addc_u32 s41, s37, 0
	s_mov_b32 s20, s21
	s_add_u32 m0, s32, 0x0
	s_nop 0
	global_load_lds_dwordx4 v192, s[36:37]
	s_add_u32 m0, s32, 0x1000
	s_nop 0
	global_load_lds_dwordx4 v193, s[36:37]
	s_add_u32 m0, s32, 0x2000
	s_nop 0
	global_load_lds_dwordx4 v194, s[36:37]
	s_add_u32 m0, s32, 0x3000
	s_nop 0
	global_load_lds_dwordx4 v195, s[36:37]
	s_add_u32 m0, s32, 0x4000
	s_nop 0
	global_load_lds_dwordx4 v192, s[40:41]
	s_add_u32 m0, s32, 0x5000
	s_nop 0
	global_load_lds_dwordx4 v193, s[40:41]
	s_add_u32 m0, s32, 0x6000
	s_nop 0
	global_load_lds_dwordx4 v194, s[40:41]
	s_add_u32 m0, s32, 0x7000
	s_nop 0
	global_load_lds_dwordx4 v195, s[40:41]
	s_add_u32 m0, s32, 0x8000
	s_nop 0
	global_load_lds_dwordx4 v192, s[44:45]
	s_add_u32 m0, s32, 0x9000
	s_nop 0
	global_load_lds_dwordx4 v193, s[44:45]
	s_add_u32 m0, s32, 0xa000
	s_nop 0
	global_load_lds_dwordx4 v194, s[44:45]
	s_add_u32 m0, s32, 0xb000
	s_nop 0
	global_load_lds_dwordx4 v195, s[44:45]
	s_add_u32 s36, s36, 0x80
	s_addc_u32 s37, s37, 0
	s_add_u32 s40, s40, 0x80
	s_addc_u32 s41, s41, 0
	s_add_u32 s44, s44, 0x80
	s_addc_u32 s45, s45, 0
	s_add_i32 s20, s20, 1
	s_cmp_eq_u32 s20, 32
	s_cbranch_scc1 .Lbig_wrap2
.Lbig_wrapret2:
.Lbig_nonext:
	s_setprio 1
	v_mfma_f32_16x16x32_bf16 v[0:3], v[160:163], v[128:131], v[0:3]
	v_mfma_f32_16x16x32_bf16 v[4:7], v[164:167], v[128:131], v[4:7]
	v_mfma_f32_16x16x32_bf16 v[8:11], v[168:171], v[128:131], v[8:11]
	v_mfma_f32_16x16x32_bf16 v[12:15], v[172:175], v[128:131], v[12:15]
	v_mfma_f32_16x16x32_bf16 v[16:19], v[160:163], v[132:135], v[16:19]
	v_mfma_f32_16x16x32_bf16 v[20:23], v[164:167], v[132:135], v[20:23]
	v_mfma_f32_16x16x32_bf16 v[24:27], v[168:171], v[132:135], v[24:27]
	v_mfma_f32_16x16x32_bf16 v[28:31], v[172:175], v[132:135], v[28:31]
	v_mfma_f32_16x16x32_bf16 v[32:35], v[160:163], v[136:139], v[32:35]
	v_mfma_f32_16x16x32_bf16 v[36:39], v[164:167], v[136:139], v[36:39]
	v_mfma_f32_16x16x32_bf16 v[40:43], v[168:171], v[136:139], v[40:43]
	v_mfma_f32_16x16x32_bf16 v[44:47], v[172:175], v[136:139], v[44:47]
	v_mfma_f32_16x16x32_bf16 v[48:51], v[160:163], v[140:143], v[48:51]
	v_mfma_f32_16x16x32_bf16 v[52:55], v[164:167], v[140:143], v[52:55]
	v_mfma_f32_16x16x32_bf16 v[56:59], v[168:171], v[140:143], v[56:59]
	v_mfma_f32_16x16x32_bf16 v[60:63], v[172:175], v[140:143], v[60:63]
	v_mfma_f32_16x16x32_bf16 v[64:67], v[160:163], v[144:147], v[64:67]
	v_mfma_f32_16x16x32_bf16 v[68:71], v[164:167], v[144:147], v[68:71]
	v_mfma_f32_16x16x32_bf16 v[72:75], v[168:171], v[144:147], v[72:75]
	v_mfma_f32_16x16x32_bf16 v[76:79], v[172:175], v[144:147], v[76:79]
	v_mfma_f32_16x16x32_bf16 v[80:83], v[160:163], v[148:151], v[80:83]
	v_mfma_f32_16x16x32_bf16 v[84:87], v[164:167], v[148:151], v[84:87]
	v_mfma_f32_16x16x32_bf16 v[88:91], v[168:171], v[148:151], v[88:91]
	v_mfma_f32_16x16x32_bf16 v[92:95], v[172:175], v[148:151], v[92:95]
	v_mfma_f32_16x16x32_bf16 v[96:99], v[160:163], v[152:155], v[96:99]
	v_mfma_f32_16x16x32_bf16 v[100:103], v[164:167], v[152:155], v[100:103]
	v_mfma_f32_16x16x32_bf16 v[104:107], v[168:171], v[152:155], v[104:107]
	v_mfma_f32_16x16x32_bf16 v[108:111], v[172:175], v[152:155], v[108:111]
	v_mfma_f32_16x16x32_bf16 v[112:115], v[160:163], v[156:159], v[112:115]
	v_mfma_f32_16x16x32_bf16 v[116:119], v[164:167], v[156:159], v[116:119]
	v_mfma_f32_16x16x32_bf16 v[120:123], v[168:171], v[156:159], v[120:123]
	v_mfma_f32_16x16x32_bf16 v[124:127], v[172:175], v[156:159], v[124:127]
	v_mfma_f32_16x16x32_bf16 v[0:3], v[176:179], v[204:207], v[0:3]
	v_mfma_f32_16x16x32_bf16 v[4:7], v[180:183], v[204:207], v[4:7]
	v_mfma_f32_16x16x32_bf16 v[8:11], v[184:187], v[204:207], v[8:11]
	v_mfma_f32_16x16x32_bf16 v[12:15], v[188:191], v[204:207], v[12:15]
	v_mfma_f32_16x16x32_bf16 v[16:19], v[176:179], v[208:211], v[16:19]
	v_mfma_f32_16x16x32_bf16 v[20:23], v[180:183], v[208:211], v[20:23]
	v_mfma_f32_16x16x32_bf16 v[24:27], v[184:187], v[208:211], v[24:27]
	v_mfma_f32_16x16x32_bf16 v[28:31], v[188:191], v[208:211], v[28:31]
	v_mfma_f32_16x16x32_bf16 v[32:35], v[176:179], v[212:215], v[32:35]
	v_mfma_f32_16x16x32_bf16 v[36:39], v[180:183], v[212:215], v[36:39]
	v_mfma_f32_16x16x32_bf16 v[40:43], v[184:187], v[212:215], v[40:43]
	v_mfma_f32_16x16x32_bf16 v[44:47], v[188:191], v[212:215], v[44:47]
	v_mfma_f32_16x16x32_bf16 v[48:51], v[176:179], v[216:219], v[48:51]
	v_mfma_f32_16x16x32_bf16 v[52:55], v[180:183], v[216:219], v[52:55]
	v_mfma_f32_16x16x32_bf16 v[56:59], v[184:187], v[216:219], v[56:59]
	v_mfma_f32_16x16x32_bf16 v[60:63], v[188:191], v[216:219], v[60:63]
	v_mfma_f32_16x16x32_bf16 v[64:67], v[176:179], v[220:223], v[64:67]
	v_mfma_f32_16x16x32_bf16 v[68:71], v[180:183], v[220:223], v[68:71]
	v_mfma_f32_16x16x32_bf16 v[72:75], v[184:187], v[220:223], v[72:75]
	v_mfma_f32_16x16x32_bf16 v[76:79], v[188:191], v[220:223], v[76:79]
	v_mfma_f32_16x16x32_bf16 v[80:83], v[176:179], v[224:227], v[80:83]
	v_mfma_f32_16x16x32_bf16 v[84:87], v[180:183], v[224:227], v[84:87]
	v_mfma_f32_16x16x32_bf16 v[88:91], v[184:187], v[224:227], v[88:91]
	v_mfma_f32_16x16x32_bf16 v[92:95], v[188:191], v[224:227], v[92:95]
	v_mfma_f32_16x16x32_bf16 v[96:99], v[176:179], v[228:231], v[96:99]
	v_mfma_f32_16x16x32_bf16 v[100:103], v[180:183], v[228:231], v[100:103]
	v_mfma_f32_16x16x32_bf16 v[104:107], v[184:187], v[228:231], v[104:107]
	v_mfma_f32_16x16x32_bf16 v[108:111], v[188:191], v[228:231], v[108:111]
	v_mfma_f32_16x16x32_bf16 v[112:115], v[176:179], v[232:235], v[112:115]
	v_mfma_f32_16x16x32_bf16 v[116:119], v[180:183], v[232:235], v[116:119]
	v_mfma_f32_16x16x32_bf16 v[120:123], v[184:187], v[232:235], v[120:123]
	v_mfma_f32_16x16x32_bf16 v[124:127], v[188:191], v[232:235], v[124:127]
	s_setprio 0
	s_lshr_b32 s51, s90, 6
	s_lshl_b32 s51, s51, 7
	s_and_b32 s17, s90, 63
	s_lshl_b32 s17, s17, 8
	s_mov_b32 s16, 0x1b00
	s_mov_b32 s18, 0
	s_mov_b32 s19, 0
	s_cmp_lt_u32 s51, 0xd80
	s_cbranch_scc1 .Lbig_reg
	s_mov_b32 s16, 0x1900
	s_mov_b32 s18, 0x6c00000
	s_mov_b32 s19, 0xd80
	s_cmp_lt_u32 s51, 0x1a00
	s_cbranch_scc1 .Lbig_reg
	s_mov_b32 s16, 0x2000
	s_mov_b32 s18, 0xd000000
	s_mov_b32 s19, 0x1a00
.Lbig_reg:
	s_sub_u32 s51, s51, s19
	s_lshl_b32 s51, s51, 1
	s_mul_i32 s17, s17, s16
	s_add_u32 s17, s17, s51
	s_add_u32 s17, s17, s18
	s_add_u32 s14, s94, s17
	s_addc_u32 s15, s95, 0
	s_lshl_b32 s16, s16, 4
	v_mul_lo_u32 v203, v201, s16
	v_lshrrev_b32_e32 v203, 4, v203
	v_add_u32_e32 v203, v203, v202
	v_cvt_pk_bf16_f32 v240, v0, v1
	v_cvt_pk_bf16_f32 v241, v2, v3
	global_store_dwordx2 v203, v[240:241], s[14:15]
	v_cvt_pk_bf16_f32 v236, v4, v5
	v_cvt_pk_bf16_f32 v237, v6, v7
	global_store_dwordx2 v203, v[236:237], s[14:15] offset:32
	v_cvt_pk_bf16_f32 v240, v8, v9
	v_cvt_pk_bf16_f32 v241, v10, v11
	global_store_dwordx2 v203, v[240:241], s[14:15] offset:64
	v_cvt_pk_bf16_f32 v236, v12, v13
	v_cvt_pk_bf16_f32 v237, v14, v15
	global_store_dwordx2 v203, v[236:237], s[14:15] offset:96
	s_add_u32 s14, s14, s16
	s_addc_u32 s15, s15, 0
	v_cvt_pk_bf16_f32 v240, v16, v17
	v_cvt_pk_bf16_f32 v241, v18, v19
	global_store_dwordx2 v203, v[240:241], s[14:15]
	v_cvt_pk_bf16_f32 v236, v20, v21
	v_cvt_pk_bf16_f32 v237, v22, v23
	global_store_dwordx2 v203, v[236:237], s[14:15] offset:32
	v_cvt_pk_bf16_f32 v240, v24, v25
	v_cvt_pk_bf16_f32 v241, v26, v27
	global_store_dwordx2 v203, v[240:241], s[14:15] offset:64
	v_cvt_pk_bf16_f32 v236, v28, v29
	v_cvt_pk_bf16_f32 v237, v30, v31
	global_store_dwordx2 v203, v[236:237], s[14:15] offset:96
	s_add_u32 s14, s14, s16
	s_addc_u32 s15, s15, 0
	v_cvt_pk_bf16_f32 v240, v32, v33
	v_cvt_pk_bf16_f32 v241, v34, v35
	global_store_dwordx2 v203, v[240:241], s[14:15]
	v_cvt_pk_bf16_f32 v236, v36, v37
	v_cvt_pk_bf16_f32 v237, v38, v39
	global_store_dwordx2 v203, v[236:237], s[14:15] offset:32
	v_cvt_pk_bf16_f32 v240, v40, v41
	v_cvt_pk_bf16_f32 v241, v42, v43
	global_store_dwordx2 v203, v[240:241], s[14:15] offset:64
	v_cvt_pk_bf16_f32 v236, v44, v45
	v_cvt_pk_bf16_f32 v237, v46, v47
	global_store_dwordx2 v203, v[236:237], s[14:15] offset:96
	s_add_u32 s14, s14, s16
	s_addc_u32 s15, s15, 0
	v_cvt_pk_bf16_f32 v240, v48, v49
	v_cvt_pk_bf16_f32 v241, v50, v51
	global_store_dwordx2 v203, v[240:241], s[14:15]
	v_cvt_pk_bf16_f32 v236, v52, v53
	v_cvt_pk_bf16_f32 v237, v54, v55
	global_store_dwordx2 v203, v[236:237], s[14:15] offset:32
	v_cvt_pk_bf16_f32 v240, v56, v57
	v_cvt_pk_bf16_f32 v241, v58, v59
	global_store_dwordx2 v203, v[240:241], s[14:15] offset:64
	v_cvt_pk_bf16_f32 v236, v60, v61
	v_cvt_pk_bf16_f32 v237, v62, v63
	global_store_dwordx2 v203, v[236:237], s[14:15] offset:96
	s_add_u32 s14, s14, s16
	s_addc_u32 s15, s15, 0
	v_cvt_pk_bf16_f32 v240, v64, v65
	v_cvt_pk_bf16_f32 v241, v66, v67
	global_store_dwordx2 v203, v[240:241], s[14:15]
	v_cvt_pk_bf16_f32 v236, v68, v69
	v_cvt_pk_bf16_f32 v237, v70, v71
	global_store_dwordx2 v203, v[236:237], s[14:15] offset:32
	v_cvt_pk_bf16_f32 v240, v72, v73
	v_cvt_pk_bf16_f32 v241, v74, v75
	global_store_dwordx2 v203, v[240:241], s[14:15] offset:64
	v_cvt_pk_bf16_f32 v236, v76, v77
	v_cvt_pk_bf16_f32 v237, v78, v79
	global_store_dwordx2 v203, v[236:237], s[14:15] offset:96
	s_add_u32 s14, s14, s16
	s_addc_u32 s15, s15, 0
	v_cvt_pk_bf16_f32 v240, v80, v81
	v_cvt_pk_bf16_f32 v241, v82, v83
	global_store_dwordx2 v203, v[240:241], s[14:15]
	v_cvt_pk_bf16_f32 v236, v84, v85
	v_cvt_pk_bf16_f32 v237, v86, v87
	global_store_dwordx2 v203, v[236:237], s[14:15] offset:32
	v_cvt_pk_bf16_f32 v240, v88, v89
	v_cvt_pk_bf16_f32 v241, v90, v91
	global_store_dwordx2 v203, v[240:241], s[14:15] offset:64
	v_cvt_pk_bf16_f32 v236, v92, v93
	v_cvt_pk_bf16_f32 v237, v94, v95
	global_store_dwordx2 v203, v[236:237], s[14:15] offset:96
	s_add_u32 s14, s14, s16
	s_addc_u32 s15, s15, 0
	v_cvt_pk_bf16_f32 v240, v96, v97
	v_cvt_pk_bf16_f32 v241, v98, v99
	global_store_dwordx2 v203, v[240:241], s[14:15]
	v_cvt_pk_bf16_f32 v236, v100, v101
	v_cvt_pk_bf16_f32 v237, v102, v103
	global_store_dwordx2 v203, v[236:237], s[14:15] offset:32
	v_cvt_pk_bf16_f32 v240, v104, v105
	v_cvt_pk_bf16_f32 v241, v106, v107
	global_store_dwordx2 v203, v[240:241], s[14:15] offset:64
	v_cvt_pk_bf16_f32 v236, v108, v109
	v_cvt_pk_bf16_f32 v237, v110, v111
	global_store_dwordx2 v203, v[236:237], s[14:15] offset:96
	s_add_u32 s14, s14, s16
	s_addc_u32 s15, s15, 0
	v_cvt_pk_bf16_f32 v240, v112, v113
	v_cvt_pk_bf16_f32 v241, v114, v115
	global_store_dwordx2 v203, v[240:241], s[14:15]
	v_cvt_pk_bf16_f32 v236, v116, v117
	v_cvt_pk_bf16_f32 v237, v118, v119
	global_store_dwordx2 v203, v[236:237], s[14:15] offset:32
	v_cvt_pk_bf16_f32 v240, v120, v121
	v_cvt_pk_bf16_f32 v241, v122, v123
	global_store_dwordx2 v203, v[240:241], s[14:15] offset:64
	v_cvt_pk_bf16_f32 v236, v124, v125
	v_cvt_pk_bf16_f32 v237, v126, v127
	global_store_dwordx2 v203, v[236:237], s[14:15] offset:96
	s_add_u32 s90, s90, 0x200
	s_cmp_lt_u32 s90, 0x1400
	s_cbranch_scc1 .Lbig_tile
	s_waitcnt vmcnt(0)
	s_mov_b32 s91, 1
	s_branch .Lbig_skip
.Lbig_wrap0:
	s_mov_b32 s20, 0
	s_sub_u32 s36, s36, 0x1000
	s_subb_u32 s37, s37, 0
	s_sub_u32 s40, s40, 0x1000
	s_subb_u32 s41, s41, 0
	s_sub_u32 s44, s44, 0x1000
	s_subb_u32 s45, s45, 0
	s_branch .Lbig_wrapret0
